# attention unit epilogue: 16 row-per-lane dwordx2 stores widened to 8 dwordx4 stores via v_permlane32_swap pairs (asm guide 7.3), counted waits adjusted
# baseline (speedup 1.0000x reference)
.LBB0_1151:
	s_andn2_b64 vcc, exec, s[4:5]
	s_waitcnt vmcnt(0) lgkmcnt(0)
	s_barrier
	s_cbranch_vccnz .LBB0_1153
	s_lshl_b32 s8, s35, 7
	s_and_b32 s8, s8, 0xf80
	s_add_i32 s8, s8, s18
	s_ashr_i32 s9, s8, 31
	v_lshl_add_u64 v[64:65], v[184:185], 0, s[8:9]
	v_lshlrev_b64 v[64:65], 11, v[64:65]
	v_lshl_add_u64 v[64:65], v[64:65], 0, s[52:53]
	v_lshlrev_b64 v[80:81], 1, v[64:65]
	v_lshl_add_u64 v[68:69], v[190:191], 0, v[80:81]
	global_load_dwordx2 v[98:99], v[68:69], off
	ds_read2st64_b32 v[70:71], v245 offset1:1
	ds_read2st64_b32 v[72:73], v245 offset0:2 offset1:3
	ds_read2st64_b32 v[76:77], v245 offset0:4 offset1:5
	ds_read2st64_b32 v[74:75], v245 offset0:6 offset1:7
	ds_read2st64_b32 v[126:127], v245 offset0:8 offset1:9
	ds_read2st64_b32 v[144:145], v245 offset0:10 offset1:11
	ds_read2st64_b32 v[146:147], v245 offset0:12 offset1:13
	ds_read2st64_b32 v[148:149], v245 offset0:14 offset1:15
	ds_read2st64_b32 v[150:151], v245 offset0:16 offset1:17
	ds_read2st64_b32 v[152:153], v245 offset0:18 offset1:19
	ds_read2st64_b32 v[124:125], v245 offset0:20 offset1:21
	ds_read2st64_b32 v[154:155], v245 offset0:22 offset1:23
	ds_read2st64_b32 v[120:121], v245 offset0:24 offset1:25
	ds_read2st64_b32 v[122:123], v245 offset0:26 offset1:27
	ds_read2st64_b32 v[116:117], v245 offset0:28 offset1:29
	ds_read2st64_b32 v[118:119], v245 offset0:30 offset1:31
	ds_read2st64_b32 v[110:111], v245 offset0:32 offset1:33
	ds_read2st64_b32 v[114:115], v245 offset0:34 offset1:35
	ds_read2st64_b32 v[104:105], v245 offset0:36 offset1:37
	ds_read2st64_b32 v[112:113], v245 offset0:38 offset1:39
	ds_read2st64_b32 v[96:97], v245 offset0:40 offset1:41
	ds_read2st64_b32 v[108:109], v245 offset0:42 offset1:43
	ds_read2st64_b32 v[92:93], v245 offset0:44 offset1:45
	ds_read2st64_b32 v[102:103], v245 offset0:46 offset1:47
	ds_read2st64_b32 v[86:87], v245 offset0:56 offset1:57
	ds_read2st64_b32 v[88:89], v245 offset0:58 offset1:59
	ds_read2st64_b32 v[82:83], v245 offset0:60 offset1:61
	ds_read2st64_b32 v[84:85], v245 offset0:62 offset1:63
	ds_read2st64_b32 v[94:95], v245 offset0:48 offset1:49
	ds_read2st64_b32 v[106:107], v245 offset0:50 offset1:51
	ds_read2st64_b32 v[90:91], v245 offset0:52 offset1:53
	ds_read2st64_b32 v[100:101], v245 offset0:54 offset1:55
	s_waitcnt lgkmcnt(4)
	v_pk_fma_f32 v[14:15], v[14:15], v[78:79], v[84:85] op_sel_hi:[1,0,1] neg_lo:[0,0,1] neg_hi:[0,0,1]
	v_pk_fma_f32 v[84:85], v[48:49], v[78:79], v[70:71] op_sel_hi:[1,0,1] neg_lo:[0,0,1] neg_hi:[0,0,1]
	v_pk_fma_f32 v[48:49], v[40:41], v[78:79], v[120:121] op_sel_hi:[1,0,1] neg_lo:[0,0,1] neg_hi:[0,0,1]
	v_pk_fma_f32 v[40:41], v[46:47], v[78:79], v[118:119] op_sel_hi:[1,0,1] neg_lo:[0,0,1] neg_hi:[0,0,1]
	v_pk_fma_f32 v[46:47], v[18:19], v[78:79], v[114:115] op_sel_hi:[1,0,1] neg_lo:[0,0,1] neg_hi:[0,0,1]
	v_pk_fma_f32 v[12:13], v[12:13], v[78:79], v[82:83] op_sel_hi:[1,0,1] neg_lo:[0,0,1] neg_hi:[0,0,1]
	v_pk_fma_f32 v[82:83], v[50:51], v[78:79], v[72:73] op_sel_hi:[1,0,1] neg_lo:[0,0,1] neg_hi:[0,0,1]
	v_pk_fma_f32 v[72:73], v[32:33], v[78:79], v[150:151] op_sel_hi:[1,0,1] neg_lo:[0,0,1] neg_hi:[0,0,1]
	v_pk_fma_f32 v[74:75], v[54:55], v[78:79], v[74:75] op_sel_hi:[1,0,1] neg_lo:[0,0,1] neg_hi:[0,0,1]
	v_pk_fma_f32 v[76:77], v[52:53], v[78:79], v[76:77] op_sel_hi:[1,0,1] neg_lo:[0,0,1] neg_hi:[0,0,1]
	v_pk_fma_f32 v[58:59], v[58:59], v[78:79], v[144:145] op_sel_hi:[1,0,1] neg_lo:[0,0,1] neg_hi:[0,0,1]
	v_pk_fma_f32 v[70:71], v[56:57], v[78:79], v[126:127] op_sel_hi:[1,0,1] neg_lo:[0,0,1] neg_hi:[0,0,1]
	v_pk_fma_f32 v[56:57], v[62:63], v[78:79], v[148:149] op_sel_hi:[1,0,1] neg_lo:[0,0,1] neg_hi:[0,0,1]
	v_pk_fma_f32 v[62:63], v[60:61], v[78:79], v[146:147] op_sel_hi:[1,0,1] neg_lo:[0,0,1] neg_hi:[0,0,1]
	v_pk_fma_f32 v[60:61], v[34:35], v[78:79], v[152:153] op_sel_hi:[1,0,1] neg_lo:[0,0,1] neg_hi:[0,0,1]
	v_pk_fma_f32 v[52:53], v[38:39], v[78:79], v[154:155] op_sel_hi:[1,0,1] neg_lo:[0,0,1] neg_hi:[0,0,1]
	v_pk_fma_f32 v[54:55], v[36:37], v[78:79], v[124:125] op_sel_hi:[1,0,1] neg_lo:[0,0,1] neg_hi:[0,0,1]
	v_pk_fma_f32 v[42:43], v[42:43], v[78:79], v[122:123] op_sel_hi:[1,0,1] neg_lo:[0,0,1] neg_hi:[0,0,1]
	v_pk_fma_f32 v[44:45], v[44:45], v[78:79], v[116:117] op_sel_hi:[1,0,1] neg_lo:[0,0,1] neg_hi:[0,0,1]
	v_pk_mul_f32 v[122:123], v[84:85], v[84:85]
	global_load_dwordx4 v[64:67], v[188:189], off
	v_pk_mul_f32 v[120:121], v[82:83], v[82:83]
	v_pk_mul_f32 v[126:127], v[76:77], v[76:77]
	v_pk_mul_f32 v[124:125], v[74:75], v[74:75]
	v_pk_mul_f32 v[146:147], v[70:71], v[70:71]
	v_pk_mul_f32 v[144:145], v[58:59], v[58:59]
	v_pk_mul_f32 v[150:151], v[62:63], v[62:63]
	v_pk_mul_f32 v[148:149], v[56:57], v[56:57]
	v_pk_mul_f32 v[154:155], v[72:73], v[72:73]
	v_pk_mul_f32 v[152:153], v[60:61], v[60:61]
	v_pk_mul_f32 v[158:159], v[54:55], v[54:55]
	v_pk_mul_f32 v[156:157], v[52:53], v[52:53]
	v_pk_mul_f32 v[162:163], v[48:49], v[48:49]
	v_pk_mul_f32 v[160:161], v[42:43], v[42:43]
	v_pk_mul_f32 v[166:167], v[44:45], v[44:45]
	v_pk_mul_f32 v[164:165], v[40:41], v[40:41]
	v_pk_mul_f32 v[172:173], v[46:47], v[46:47]
	v_pk_mul_f32 v[116:117], v[12:13], v[12:13]
	v_pk_mul_f32 v[118:119], v[14:15], v[14:15]
	global_load_dwordx2 v[114:115], v[68:69], off offset:16
	s_mov_b32 s8, 0x800000
	s_waitcnt vmcnt(2)
	v_lshlrev_b32_e32 v168, 16, v98
	v_and_b32_e32 v169, 0xffff0000, v98
	v_lshlrev_b32_e32 v98, 16, v99
	v_mul_f32_e32 v18, 0xbfb8aa3b, v168
	v_mul_f32_e32 v19, 0xbfb8aa3b, v169
	v_mul_f32_e32 v32, 0xbfb8aa3b, v98
	v_exp_f32_e32 v18, v18
	v_exp_f32_e32 v19, v19
	v_exp_f32_e32 v79, v32
	v_and_b32_e32 v99, 0xffff0000, v99
	v_mul_f32_e32 v33, 0xbfb8aa3b, v99
	v_add_f32_e32 v18, 1.0, v18
	v_add_f32_e32 v19, 1.0, v19
	v_exp_f32_e32 v174, v33
	v_rcp_f32_e32 v170, v18
	v_rcp_f32_e32 v171, v19
	v_pk_fma_f32 v[50:51], v[16:17], v[78:79], v[110:111] op_sel_hi:[1,0,1] neg_lo:[0,0,1] neg_hi:[0,0,1]
	v_pk_fma_f32 v[36:37], v[22:23], v[78:79], v[112:113] op_sel_hi:[1,0,1] neg_lo:[0,0,1] neg_hi:[0,0,1]
	v_pk_fma_f32 v[38:39], v[20:21], v[78:79], v[104:105] op_sel_hi:[1,0,1] neg_lo:[0,0,1] neg_hi:[0,0,1]
	v_pk_fma_f32 v[32:33], v[26:27], v[78:79], v[108:109] op_sel_hi:[1,0,1] neg_lo:[0,0,1] neg_hi:[0,0,1]
	v_pk_fma_f32 v[34:35], v[24:25], v[78:79], v[96:97] op_sel_hi:[1,0,1] neg_lo:[0,0,1] neg_hi:[0,0,1]
	v_pk_fma_f32 v[24:25], v[30:31], v[78:79], v[102:103] op_sel_hi:[1,0,1] neg_lo:[0,0,1] neg_hi:[0,0,1]
	v_pk_fma_f32 v[26:27], v[28:29], v[78:79], v[92:93] op_sel_hi:[1,0,1] neg_lo:[0,0,1] neg_hi:[0,0,1]
	s_waitcnt lgkmcnt(2)
	v_pk_fma_f32 v[20:21], v[2:3], v[78:79], v[106:107] op_sel_hi:[1,0,1] neg_lo:[0,0,1] neg_hi:[0,0,1]
	v_pk_fma_f32 v[22:23], v[0:1], v[78:79], v[94:95] op_sel_hi:[1,0,1] neg_lo:[0,0,1] neg_hi:[0,0,1]
	s_waitcnt lgkmcnt(0)
	v_pk_fma_f32 v[16:17], v[6:7], v[78:79], v[100:101] op_sel_hi:[1,0,1] neg_lo:[0,0,1] neg_hi:[0,0,1]
	v_pk_fma_f32 v[18:19], v[4:5], v[78:79], v[90:91] op_sel_hi:[1,0,1] neg_lo:[0,0,1] neg_hi:[0,0,1]
	v_pk_fma_f32 v[4:5], v[10:11], v[78:79], v[88:89] op_sel_hi:[1,0,1] neg_lo:[0,0,1] neg_hi:[0,0,1]
	v_pk_fma_f32 v[6:7], v[8:9], v[78:79], v[86:87] op_sel_hi:[1,0,1] neg_lo:[0,0,1] neg_hi:[0,0,1]
	v_add_f32_e32 v78, v122, v123
	v_add_f32_e32 v78, v78, v120
	v_add_f32_e32 v78, v78, v121
	v_add_f32_e32 v78, v78, v126
	v_add_f32_e32 v78, v78, v127
	v_add_f32_e32 v78, v78, v124
	v_add_f32_e32 v78, v78, v125
	v_add_f32_e32 v78, v78, v146
	v_add_f32_e32 v78, v78, v147
	v_add_f32_e32 v78, v78, v144
	v_add_f32_e32 v78, v78, v145
	v_add_f32_e32 v78, v78, v150
	v_add_f32_e32 v78, v78, v151
	v_add_f32_e32 v78, v78, v148
	v_add_f32_e32 v78, v78, v149
	v_add_f32_e32 v78, v78, v154
	v_add_f32_e32 v78, v78, v155
	v_add_f32_e32 v78, v78, v152
	v_add_f32_e32 v78, v78, v153
	v_add_f32_e32 v78, v78, v158
	v_add_f32_e32 v78, v78, v159
	v_add_f32_e32 v78, v78, v156
	v_add_f32_e32 v78, v78, v157
	v_add_f32_e32 v78, v78, v162
	v_add_f32_e32 v78, v78, v163
	v_add_f32_e32 v78, v78, v160
	v_add_f32_e32 v78, v78, v161
	v_add_f32_e32 v78, v78, v166
	v_add_f32_e32 v78, v78, v167
	v_add_f32_e32 v78, v78, v164
	v_pk_mul_f32 v[110:111], v[50:51], v[50:51]
	v_add_f32_e32 v78, v78, v165
	v_add_f32_e32 v78, v78, v110
	v_add_f32_e32 v78, v78, v111
	v_add_f32_e32 v78, v78, v172
	v_pk_mul_f32 v[104:105], v[38:39], v[38:39]
	v_add_f32_e32 v78, v78, v173
	v_add_f32_e32 v78, v78, v104
	v_pk_mul_f32 v[112:113], v[36:37], v[36:37]
	v_add_f32_e32 v78, v78, v105
	v_add_f32_e32 v78, v78, v112
	v_pk_mul_f32 v[96:97], v[34:35], v[34:35]
	v_add_f32_e32 v78, v78, v113
	v_add_f32_e32 v78, v78, v96
	v_pk_mul_f32 v[108:109], v[32:33], v[32:33]
	v_add_f32_e32 v78, v78, v97
	v_add_f32_e32 v78, v78, v108
	v_pk_mul_f32 v[28:29], v[26:27], v[26:27]
	v_add_f32_e32 v78, v78, v109
	v_add_f32_e32 v28, v78, v28
	v_pk_mul_f32 v[30:31], v[24:25], v[24:25]
	v_add_f32_e32 v28, v28, v29
	v_add_f32_e32 v28, v28, v30
	v_pk_mul_f32 v[0:1], v[22:23], v[22:23]
	v_add_f32_e32 v28, v28, v31
	v_add_f32_e32 v0, v28, v0
	v_pk_mul_f32 v[2:3], v[20:21], v[20:21]
	v_add_f32_e32 v0, v0, v1
	v_add_f32_e32 v0, v0, v2
	v_pk_mul_f32 v[90:91], v[18:19], v[18:19]
	v_add_f32_e32 v0, v0, v3
	v_add_f32_e32 v0, v0, v90
	v_pk_mul_f32 v[92:93], v[16:17], v[16:17]
	v_add_f32_e32 v0, v0, v91
	v_add_f32_e32 v0, v0, v92
	v_pk_mul_f32 v[8:9], v[6:7], v[6:7]
	v_add_f32_e32 v0, v0, v93
	v_add_f32_e32 v0, v0, v8
	v_pk_mul_f32 v[10:11], v[4:5], v[4:5]
	v_add_f32_e32 v0, v0, v9
	v_add_f32_e32 v0, v0, v10
	v_add_f32_e32 v0, v0, v11
	v_add_f32_e32 v0, v0, v116
	v_add_f32_e32 v0, v0, v117
	v_add_f32_e32 v0, v0, v118
	v_add_f32_e32 v2, v0, v119
	ds_bpermute_b32 v3, v244, v2
	v_add_f32_e32 v0, 1.0, v79
	v_add_f32_e32 v1, 1.0, v174
	v_rcp_f32_e32 v0, v0
	v_rcp_f32_e32 v1, v1
	s_waitcnt lgkmcnt(0)
	v_add_f32_e32 v2, v2, v3
	v_fmamk_f32 v2, v2, 0x3c000000, v233
	v_mul_f32_e32 v3, 0x4b800000, v2
	v_cmp_gt_f32_e32 vcc, s8, v2
	v_pk_mul_f32 v[0:1], v[0:1], v[98:99]
	v_lshl_add_u64 v[8:9], v[192:193], 0, v[80:81]
	v_mbcnt_lo_u32_b32 v134, -1, 0
	v_mbcnt_hi_u32_b32 v134, -1, v134
	v_and_b32_e32 v134, 32, v134
	v_lshrrev_b32_e32 v134, 2, v134
	v_mov_b32_e32 v135, 0
	v_lshl_add_u64 v[132:133], v[8:9], 0, v[134:135]
	v_cndmask_b32_e32 v2, v2, v3, vcc
	v_rsq_f32_e32 v10, v2
	v_pk_mul_f32 v[2:3], v[170:171], v[168:169]
	s_waitcnt vmcnt(0)
	v_lshlrev_b32_e32 v30, 16, v114
	v_and_b32_e32 v31, 0xffff0000, v114
	v_mul_f32_e32 v11, 0x45800000, v10
	v_cndmask_b32_e32 v10, v10, v11, vcc
	v_mul_f32_e32 v10, 0x3f24fd5c, v10
	v_pk_mul_f32 v[28:29], v[84:85], v[10:11] op_sel_hi:[1,0]
	s_nop 0
	v_pk_mul_f32 v[28:29], v[64:65], v[28:29]
	v_mul_f32_e32 v65, 0xbfb8aa3b, v31
	v_pk_mul_f32 v[2:3], v[2:3], v[28:29]
	v_pk_mul_f32 v[28:29], v[82:83], v[10:11] op_sel_hi:[1,0]
	v_cvt_pk_bf16_f32 v128, v2, v3
	v_pk_mul_f32 v[28:29], v[66:67], v[28:29]
	v_mul_f32_e32 v11, 0xbfb8aa3b, v30
	v_pk_mul_f32 v[0:1], v[0:1], v[28:29]
	v_exp_f32_e32 v11, v11
	v_cvt_pk_bf16_f32 v129, v0, v1
	global_load_dwordx4 v[0:3], v[188:189], off offset:32
	s_nop 0
	global_load_dwordx2 v[28:29], v[68:69], off offset:32
	v_exp_f32_e32 v67, v65
	v_lshlrev_b32_e32 v64, 16, v115
	v_add_f32_e32 v11, 1.0, v11
	v_and_b32_e32 v65, 0xffff0000, v115
	v_rcp_f32_e32 v66, v11
	v_add_f32_e32 v11, 1.0, v67
	v_mul_f32_e32 v67, 0xbfb8aa3b, v64
	v_exp_f32_e32 v78, v67
	v_mul_f32_e32 v67, 0xbfb8aa3b, v65
	v_exp_f32_e32 v79, v67
	v_rcp_f32_e32 v67, v11
	v_add_f32_e32 v11, 1.0, v78
	v_rcp_f32_e32 v78, v11
	v_add_f32_e32 v11, 1.0, v79
	v_rcp_f32_e32 v79, v11
	v_pk_mul_f32 v[30:31], v[66:67], v[30:31]
	v_pk_mul_f32 v[66:67], v[76:77], v[10:11] op_sel_hi:[1,0]
	v_pk_mul_f32 v[64:65], v[78:79], v[64:65]
	s_waitcnt vmcnt(1)
	v_pk_mul_f32 v[0:1], v[0:1], v[66:67]
	s_nop 0
	v_pk_mul_f32 v[0:1], v[30:31], v[0:1]
	v_pk_mul_f32 v[30:31], v[74:75], v[10:11] op_sel_hi:[1,0]
	v_cvt_pk_bf16_f32 v130, v0, v1
	v_pk_mul_f32 v[2:3], v[2:3], v[30:31]
	s_nop 0
	v_pk_mul_f32 v[2:3], v[2:3], v[64:65]
	s_waitcnt vmcnt(0)
	v_lshlrev_b32_e32 v64, 16, v28
	v_cvt_pk_bf16_f32 v131, v2, v3
	s_nop 1
	v_permlane32_swap_b32 v128, v130
	v_permlane32_swap_b32 v129, v131
	global_store_dwordx4 v[132:133], v[128:131], off
	global_load_dwordx4 v[0:3], v[188:189], off offset:64
	s_nop 0
	global_load_dwordx2 v[30:31], v[68:69], off offset:48
	v_and_b32_e32 v65, 0xffff0000, v28
	v_mul_f32_e32 v11, 0xbfb8aa3b, v64
	v_exp_f32_e32 v11, v11
	v_mul_f32_e32 v66, 0xbfb8aa3b, v65
	v_exp_f32_e32 v67, v66
	v_lshlrev_b32_e32 v28, 16, v29
	v_add_f32_e32 v11, 1.0, v11
	v_and_b32_e32 v29, 0xffff0000, v29
	v_rcp_f32_e32 v66, v11
	v_add_f32_e32 v11, 1.0, v67
	v_mul_f32_e32 v67, 0xbfb8aa3b, v28
	v_exp_f32_e32 v74, v67
	v_mul_f32_e32 v67, 0xbfb8aa3b, v29
	v_exp_f32_e32 v75, v67
	v_rcp_f32_e32 v67, v11
	v_add_f32_e32 v11, 1.0, v74
	v_rcp_f32_e32 v74, v11
	v_add_f32_e32 v11, 1.0, v75
	v_rcp_f32_e32 v75, v11
	v_pk_mul_f32 v[64:65], v[66:67], v[64:65]
	v_pk_mul_f32 v[66:67], v[70:71], v[10:11] op_sel_hi:[1,0]
	v_pk_mul_f32 v[58:59], v[58:59], v[10:11] op_sel_hi:[1,0]
	v_pk_mul_f32 v[28:29], v[74:75], v[28:29]
	s_waitcnt vmcnt(1)
	v_pk_mul_f32 v[0:1], v[66:67], v[0:1]
	v_pk_mul_f32 v[2:3], v[58:59], v[2:3]
	v_pk_mul_f32 v[0:1], v[0:1], v[64:65]
	v_pk_mul_f32 v[2:3], v[2:3], v[28:29]
	v_cvt_pk_bf16_f32 v128, v0, v1
	v_cvt_pk_bf16_f32 v129, v2, v3
	global_load_dwordx4 v[0:3], v[188:189], off offset:96
	s_nop 0
	global_load_dwordx2 v[28:29], v[68:69], off offset:64
	s_waitcnt vmcnt(2)
	v_lshlrev_b32_e32 v58, 16, v30
	v_and_b32_e32 v59, 0xffff0000, v30
	v_lshlrev_b32_e32 v30, 16, v31
	v_and_b32_e32 v31, 0xffff0000, v31
	v_mul_f32_e32 v11, 0xbfb8aa3b, v58
	v_mul_f32_e32 v64, 0xbfb8aa3b, v59
	v_mul_f32_e32 v65, 0xbfb8aa3b, v30
	v_mul_f32_e32 v66, 0xbfb8aa3b, v31
	v_exp_f32_e32 v11, v11
	v_exp_f32_e32 v64, v64
	v_exp_f32_e32 v65, v65
	v_exp_f32_e32 v66, v66
	v_add_f32_e32 v11, 1.0, v11
	v_add_f32_e32 v67, 1.0, v64
	v_add_f32_e32 v70, 1.0, v65
	v_add_f32_e32 v71, 1.0, v66
	v_rcp_f32_e32 v64, v11
	v_rcp_f32_e32 v65, v67
	v_rcp_f32_e32 v66, v70
	v_rcp_f32_e32 v67, v71
	v_pk_mul_f32 v[62:63], v[62:63], v[10:11] op_sel_hi:[1,0]
	v_pk_mul_f32 v[56:57], v[56:57], v[10:11] op_sel_hi:[1,0]
	v_pk_mul_f32 v[58:59], v[64:65], v[58:59]
	v_pk_mul_f32 v[30:31], v[66:67], v[30:31]
	s_waitcnt vmcnt(1)
	v_pk_mul_f32 v[0:1], v[62:63], v[0:1]
	v_pk_mul_f32 v[2:3], v[56:57], v[2:3]
	v_pk_mul_f32 v[0:1], v[0:1], v[58:59]
	v_pk_mul_f32 v[2:3], v[2:3], v[30:31]
	v_cvt_pk_bf16_f32 v130, v0, v1
	v_cvt_pk_bf16_f32 v131, v2, v3
	s_nop 1
	v_permlane32_swap_b32 v128, v130
	v_permlane32_swap_b32 v129, v131
	global_store_dwordx4 v[132:133], v[128:131], off offset:32
	global_load_dwordx4 v[0:3], v[188:189], off offset:128
	s_nop 0
	global_load_dwordx2 v[30:31], v[68:69], off offset:80
	s_waitcnt vmcnt(3)
	v_lshlrev_b32_e32 v56, 16, v28
	v_and_b32_e32 v57, 0xffff0000, v28
	v_lshlrev_b32_e32 v28, 16, v29
	v_and_b32_e32 v29, 0xffff0000, v29
	v_mul_f32_e32 v11, 0xbfb8aa3b, v56
	v_mul_f32_e32 v58, 0xbfb8aa3b, v57
	v_mul_f32_e32 v59, 0xbfb8aa3b, v28
	v_mul_f32_e32 v62, 0xbfb8aa3b, v29
	v_exp_f32_e32 v11, v11
	v_exp_f32_e32 v58, v58
	v_exp_f32_e32 v59, v59
	v_exp_f32_e32 v62, v62
	v_add_f32_e32 v11, 1.0, v11
	v_add_f32_e32 v63, 1.0, v58
	v_add_f32_e32 v64, 1.0, v59
	v_add_f32_e32 v65, 1.0, v62
	v_rcp_f32_e32 v58, v11
	v_rcp_f32_e32 v59, v63
	v_rcp_f32_e32 v62, v64
	v_rcp_f32_e32 v63, v65
	v_pk_mul_f32 v[64:65], v[72:73], v[10:11] op_sel_hi:[1,0]
	v_pk_mul_f32 v[60:61], v[60:61], v[10:11] op_sel_hi:[1,0]
	v_pk_mul_f32 v[56:57], v[58:59], v[56:57]
	v_pk_mul_f32 v[28:29], v[62:63], v[28:29]
	s_waitcnt vmcnt(1)
	v_pk_mul_f32 v[0:1], v[64:65], v[0:1]
	v_pk_mul_f32 v[2:3], v[60:61], v[2:3]
	v_pk_mul_f32 v[0:1], v[0:1], v[56:57]
	v_pk_mul_f32 v[2:3], v[2:3], v[28:29]
	v_cvt_pk_bf16_f32 v128, v0, v1
	v_cvt_pk_bf16_f32 v129, v2, v3
	global_load_dwordx4 v[0:3], v[188:189], off offset:160
	s_nop 0
	global_load_dwordx2 v[28:29], v[68:69], off offset:96
	s_waitcnt vmcnt(2)
	v_lshlrev_b32_e32 v56, 16, v30
	v_and_b32_e32 v57, 0xffff0000, v30
	v_lshlrev_b32_e32 v30, 16, v31
	v_and_b32_e32 v31, 0xffff0000, v31
	v_mul_f32_e32 v11, 0xbfb8aa3b, v56
	v_mul_f32_e32 v58, 0xbfb8aa3b, v57
	v_mul_f32_e32 v59, 0xbfb8aa3b, v30
	v_mul_f32_e32 v60, 0xbfb8aa3b, v31
	v_exp_f32_e32 v11, v11
	v_exp_f32_e32 v58, v58
	v_exp_f32_e32 v59, v59
	v_exp_f32_e32 v60, v60
	v_add_f32_e32 v11, 1.0, v11
	v_add_f32_e32 v61, 1.0, v58
	v_add_f32_e32 v62, 1.0, v59
	v_add_f32_e32 v63, 1.0, v60
	v_rcp_f32_e32 v58, v11
	v_rcp_f32_e32 v59, v61
	v_rcp_f32_e32 v60, v62
	v_rcp_f32_e32 v61, v63
	v_pk_mul_f32 v[54:55], v[54:55], v[10:11] op_sel_hi:[1,0]
	v_pk_mul_f32 v[52:53], v[52:53], v[10:11] op_sel_hi:[1,0]
	v_pk_mul_f32 v[56:57], v[58:59], v[56:57]
	v_pk_mul_f32 v[30:31], v[60:61], v[30:31]
	s_waitcnt vmcnt(1)
	v_pk_mul_f32 v[0:1], v[54:55], v[0:1]
	v_pk_mul_f32 v[2:3], v[52:53], v[2:3]
	v_pk_mul_f32 v[0:1], v[0:1], v[56:57]
	v_pk_mul_f32 v[2:3], v[2:3], v[30:31]
	v_cvt_pk_bf16_f32 v130, v0, v1
	v_cvt_pk_bf16_f32 v131, v2, v3
	s_nop 1
	v_permlane32_swap_b32 v128, v130
	v_permlane32_swap_b32 v129, v131
	global_store_dwordx4 v[132:133], v[128:131], off offset:64
	global_load_dwordx4 v[0:3], v[188:189], off offset:192
	s_nop 0
	global_load_dwordx2 v[30:31], v[68:69], off offset:112
	s_waitcnt vmcnt(3)
	v_lshlrev_b32_e32 v52, 16, v28
	v_and_b32_e32 v53, 0xffff0000, v28
	v_lshlrev_b32_e32 v28, 16, v29
	v_and_b32_e32 v29, 0xffff0000, v29
	v_mul_f32_e32 v11, 0xbfb8aa3b, v52
	v_mul_f32_e32 v54, 0xbfb8aa3b, v53
	v_mul_f32_e32 v55, 0xbfb8aa3b, v28
	v_mul_f32_e32 v56, 0xbfb8aa3b, v29
	v_exp_f32_e32 v11, v11
	v_exp_f32_e32 v54, v54
	v_exp_f32_e32 v55, v55
	v_exp_f32_e32 v56, v56
	v_add_f32_e32 v11, 1.0, v11
	v_add_f32_e32 v57, 1.0, v54
	v_add_f32_e32 v58, 1.0, v55
	v_add_f32_e32 v59, 1.0, v56
	v_rcp_f32_e32 v54, v11
	v_rcp_f32_e32 v55, v57
	v_rcp_f32_e32 v56, v58
	v_rcp_f32_e32 v57, v59
	v_pk_mul_f32 v[48:49], v[48:49], v[10:11] op_sel_hi:[1,0]
	v_pk_mul_f32 v[42:43], v[42:43], v[10:11] op_sel_hi:[1,0]
	v_pk_mul_f32 v[52:53], v[54:55], v[52:53]
	v_pk_mul_f32 v[28:29], v[56:57], v[28:29]
	s_waitcnt vmcnt(1)
	v_pk_mul_f32 v[0:1], v[48:49], v[0:1]
	v_pk_mul_f32 v[2:3], v[42:43], v[2:3]
	v_pk_mul_f32 v[0:1], v[0:1], v[52:53]
	v_pk_mul_f32 v[2:3], v[2:3], v[28:29]
	v_cvt_pk_bf16_f32 v128, v0, v1
	v_cvt_pk_bf16_f32 v129, v2, v3
	global_load_dwordx4 v[0:3], v[188:189], off offset:224
	s_nop 0
	global_load_dwordx2 v[28:29], v[68:69], off offset:128
	s_waitcnt vmcnt(2)
	v_lshlrev_b32_e32 v42, 16, v30
	v_and_b32_e32 v43, 0xffff0000, v30
	v_lshlrev_b32_e32 v30, 16, v31
	v_and_b32_e32 v31, 0xffff0000, v31
	v_mul_f32_e32 v11, 0xbfb8aa3b, v42
	v_mul_f32_e32 v48, 0xbfb8aa3b, v43
	v_mul_f32_e32 v49, 0xbfb8aa3b, v30
	v_mul_f32_e32 v52, 0xbfb8aa3b, v31
	v_exp_f32_e32 v11, v11
	v_exp_f32_e32 v48, v48
	v_exp_f32_e32 v49, v49
	v_exp_f32_e32 v52, v52
	v_add_f32_e32 v11, 1.0, v11
	v_add_f32_e32 v53, 1.0, v48
	v_add_f32_e32 v54, 1.0, v49
	v_add_f32_e32 v55, 1.0, v52
	v_rcp_f32_e32 v48, v11
	v_rcp_f32_e32 v49, v53
	v_rcp_f32_e32 v52, v54
	v_rcp_f32_e32 v53, v55
	v_pk_mul_f32 v[44:45], v[44:45], v[10:11] op_sel_hi:[1,0]
	v_pk_mul_f32 v[40:41], v[40:41], v[10:11] op_sel_hi:[1,0]
	v_pk_mul_f32 v[42:43], v[48:49], v[42:43]
	v_pk_mul_f32 v[30:31], v[52:53], v[30:31]
	s_waitcnt vmcnt(1)
	v_pk_mul_f32 v[0:1], v[44:45], v[0:1]
	v_pk_mul_f32 v[2:3], v[40:41], v[2:3]
	v_pk_mul_f32 v[0:1], v[0:1], v[42:43]
	v_pk_mul_f32 v[2:3], v[2:3], v[30:31]
	v_cvt_pk_bf16_f32 v130, v0, v1
	v_cvt_pk_bf16_f32 v131, v2, v3
	s_nop 1
	v_permlane32_swap_b32 v128, v130
	v_permlane32_swap_b32 v129, v131
	global_store_dwordx4 v[132:133], v[128:131], off offset:96
	global_load_dwordx4 v[0:3], v[188:189], off offset:256
	s_nop 0
	global_load_dwordx2 v[30:31], v[68:69], off offset:144
	s_waitcnt vmcnt(3)
	v_lshlrev_b32_e32 v40, 16, v28
	v_and_b32_e32 v41, 0xffff0000, v28
	v_lshlrev_b32_e32 v28, 16, v29
	v_and_b32_e32 v29, 0xffff0000, v29
	v_mul_f32_e32 v11, 0xbfb8aa3b, v40
	v_mul_f32_e32 v42, 0xbfb8aa3b, v41
	v_mul_f32_e32 v43, 0xbfb8aa3b, v28
	v_mul_f32_e32 v44, 0xbfb8aa3b, v29
	v_exp_f32_e32 v11, v11
	v_exp_f32_e32 v42, v42
	v_exp_f32_e32 v43, v43
	v_exp_f32_e32 v44, v44
	v_add_f32_e32 v11, 1.0, v11
	v_add_f32_e32 v45, 1.0, v42
	v_add_f32_e32 v48, 1.0, v43
	v_add_f32_e32 v49, 1.0, v44
	v_rcp_f32_e32 v42, v11
	v_rcp_f32_e32 v43, v45
	v_rcp_f32_e32 v44, v48
	v_rcp_f32_e32 v45, v49
	v_pk_mul_f32 v[48:49], v[50:51], v[10:11] op_sel_hi:[1,0]
	v_pk_mul_f32 v[46:47], v[46:47], v[10:11] op_sel_hi:[1,0]
	v_pk_mul_f32 v[40:41], v[42:43], v[40:41]
	v_pk_mul_f32 v[28:29], v[44:45], v[28:29]
	s_waitcnt vmcnt(1)
	v_pk_mul_f32 v[0:1], v[48:49], v[0:1]
	v_pk_mul_f32 v[2:3], v[46:47], v[2:3]
	v_pk_mul_f32 v[0:1], v[0:1], v[40:41]
	v_pk_mul_f32 v[2:3], v[2:3], v[28:29]
	v_cvt_pk_bf16_f32 v128, v0, v1
	v_cvt_pk_bf16_f32 v129, v2, v3
	global_load_dwordx4 v[0:3], v[188:189], off offset:288
	s_nop 0
	global_load_dwordx2 v[28:29], v[68:69], off offset:160
	s_waitcnt vmcnt(2)
	v_lshlrev_b32_e32 v40, 16, v30
	v_and_b32_e32 v41, 0xffff0000, v30
	v_lshlrev_b32_e32 v30, 16, v31
	v_and_b32_e32 v31, 0xffff0000, v31
	v_mul_f32_e32 v11, 0xbfb8aa3b, v40
	v_mul_f32_e32 v42, 0xbfb8aa3b, v41
	v_mul_f32_e32 v43, 0xbfb8aa3b, v30
	v_mul_f32_e32 v44, 0xbfb8aa3b, v31
	v_exp_f32_e32 v11, v11
	v_exp_f32_e32 v42, v42
	v_exp_f32_e32 v43, v43
	v_exp_f32_e32 v44, v44
	v_add_f32_e32 v11, 1.0, v11
	v_add_f32_e32 v45, 1.0, v42
	v_add_f32_e32 v46, 1.0, v43
	v_add_f32_e32 v47, 1.0, v44
	v_rcp_f32_e32 v42, v11
	v_rcp_f32_e32 v43, v45
	v_rcp_f32_e32 v44, v46
	v_rcp_f32_e32 v45, v47
	v_pk_mul_f32 v[38:39], v[38:39], v[10:11] op_sel_hi:[1,0]
	v_pk_mul_f32 v[36:37], v[36:37], v[10:11] op_sel_hi:[1,0]
	v_pk_mul_f32 v[40:41], v[42:43], v[40:41]
	v_pk_mul_f32 v[30:31], v[44:45], v[30:31]
	s_waitcnt vmcnt(1)
	v_pk_mul_f32 v[0:1], v[38:39], v[0:1]
	v_pk_mul_f32 v[2:3], v[36:37], v[2:3]
	v_pk_mul_f32 v[0:1], v[0:1], v[40:41]
	v_pk_mul_f32 v[2:3], v[2:3], v[30:31]
	v_cvt_pk_bf16_f32 v130, v0, v1
	v_cvt_pk_bf16_f32 v131, v2, v3
	s_nop 1
	v_permlane32_swap_b32 v128, v130
	v_permlane32_swap_b32 v129, v131
	global_store_dwordx4 v[132:133], v[128:131], off offset:128
	global_load_dwordx4 v[0:3], v[188:189], off offset:320
	s_nop 0
	global_load_dwordx2 v[30:31], v[68:69], off offset:176
	s_waitcnt vmcnt(3)
	v_lshlrev_b32_e32 v36, 16, v28
	v_and_b32_e32 v37, 0xffff0000, v28
	v_lshlrev_b32_e32 v28, 16, v29
	v_and_b32_e32 v29, 0xffff0000, v29
	v_mul_f32_e32 v11, 0xbfb8aa3b, v36
	v_mul_f32_e32 v38, 0xbfb8aa3b, v37
	v_mul_f32_e32 v39, 0xbfb8aa3b, v28
	v_mul_f32_e32 v40, 0xbfb8aa3b, v29
	v_exp_f32_e32 v11, v11
	v_exp_f32_e32 v38, v38
	v_exp_f32_e32 v39, v39
	v_exp_f32_e32 v40, v40
	v_add_f32_e32 v11, 1.0, v11
	v_add_f32_e32 v41, 1.0, v38
	v_add_f32_e32 v42, 1.0, v39
	v_add_f32_e32 v43, 1.0, v40
	v_rcp_f32_e32 v38, v11
	v_rcp_f32_e32 v39, v41
	v_rcp_f32_e32 v40, v42
	v_rcp_f32_e32 v41, v43
	v_pk_mul_f32 v[34:35], v[34:35], v[10:11] op_sel_hi:[1,0]
	v_pk_mul_f32 v[32:33], v[32:33], v[10:11] op_sel_hi:[1,0]
	v_pk_mul_f32 v[36:37], v[38:39], v[36:37]
	v_pk_mul_f32 v[28:29], v[40:41], v[28:29]
	s_waitcnt vmcnt(1)
	v_pk_mul_f32 v[0:1], v[34:35], v[0:1]
	v_pk_mul_f32 v[2:3], v[32:33], v[2:3]
	v_pk_mul_f32 v[0:1], v[0:1], v[36:37]
	v_pk_mul_f32 v[2:3], v[2:3], v[28:29]
	v_cvt_pk_bf16_f32 v128, v0, v1
	v_cvt_pk_bf16_f32 v129, v2, v3
	global_load_dwordx4 v[0:3], v[188:189], off offset:352
	s_nop 0
	global_load_dwordx2 v[28:29], v[68:69], off offset:192
	s_waitcnt vmcnt(2)
	v_lshlrev_b32_e32 v32, 16, v30
	v_and_b32_e32 v33, 0xffff0000, v30
	v_lshlrev_b32_e32 v30, 16, v31
	v_and_b32_e32 v31, 0xffff0000, v31
	v_mul_f32_e32 v11, 0xbfb8aa3b, v32
	v_mul_f32_e32 v34, 0xbfb8aa3b, v33
	v_mul_f32_e32 v35, 0xbfb8aa3b, v30
	v_mul_f32_e32 v36, 0xbfb8aa3b, v31
	v_exp_f32_e32 v11, v11
	v_exp_f32_e32 v34, v34
	v_exp_f32_e32 v35, v35
	v_exp_f32_e32 v36, v36
	v_add_f32_e32 v11, 1.0, v11
	v_add_f32_e32 v37, 1.0, v34
	v_add_f32_e32 v38, 1.0, v35
	v_add_f32_e32 v39, 1.0, v36
	v_rcp_f32_e32 v34, v11
	v_rcp_f32_e32 v35, v37
	v_rcp_f32_e32 v36, v38
	v_rcp_f32_e32 v37, v39
	v_pk_mul_f32 v[26:27], v[26:27], v[10:11] op_sel_hi:[1,0]
	v_pk_mul_f32 v[24:25], v[24:25], v[10:11] op_sel_hi:[1,0]
	v_pk_mul_f32 v[32:33], v[34:35], v[32:33]
	v_pk_mul_f32 v[30:31], v[36:37], v[30:31]
	s_waitcnt vmcnt(1)
	v_pk_mul_f32 v[0:1], v[26:27], v[0:1]
	v_pk_mul_f32 v[2:3], v[24:25], v[2:3]
	v_pk_mul_f32 v[0:1], v[0:1], v[32:33]
	v_pk_mul_f32 v[2:3], v[2:3], v[30:31]
	v_cvt_pk_bf16_f32 v130, v0, v1
	v_cvt_pk_bf16_f32 v131, v2, v3
	s_nop 1
	v_permlane32_swap_b32 v128, v130
	v_permlane32_swap_b32 v129, v131
	global_store_dwordx4 v[132:133], v[128:131], off offset:160
	global_load_dwordx4 v[0:3], v[188:189], off offset:384
	s_nop 0
	global_load_dwordx2 v[24:25], v[68:69], off offset:208
	s_waitcnt vmcnt(3)
	v_lshlrev_b32_e32 v26, 16, v28
	v_and_b32_e32 v27, 0xffff0000, v28
	v_lshlrev_b32_e32 v28, 16, v29
	v_and_b32_e32 v29, 0xffff0000, v29
	v_mul_f32_e32 v11, 0xbfb8aa3b, v26
	v_mul_f32_e32 v30, 0xbfb8aa3b, v27
	v_mul_f32_e32 v31, 0xbfb8aa3b, v28
	v_mul_f32_e32 v32, 0xbfb8aa3b, v29
	v_exp_f32_e32 v11, v11
	v_exp_f32_e32 v30, v30
	v_exp_f32_e32 v31, v31
	v_exp_f32_e32 v32, v32
	v_add_f32_e32 v11, 1.0, v11
	v_add_f32_e32 v33, 1.0, v30
	v_add_f32_e32 v34, 1.0, v31
	v_add_f32_e32 v35, 1.0, v32
	v_rcp_f32_e32 v30, v11
	v_rcp_f32_e32 v31, v33
	v_rcp_f32_e32 v32, v34
	v_rcp_f32_e32 v33, v35
	v_pk_mul_f32 v[22:23], v[22:23], v[10:11] op_sel_hi:[1,0]
	v_pk_mul_f32 v[20:21], v[20:21], v[10:11] op_sel_hi:[1,0]
	v_pk_mul_f32 v[26:27], v[30:31], v[26:27]
	v_pk_mul_f32 v[28:29], v[32:33], v[28:29]
	s_waitcnt vmcnt(1)
	v_pk_mul_f32 v[0:1], v[22:23], v[0:1]
	v_pk_mul_f32 v[2:3], v[20:21], v[2:3]
	v_pk_mul_f32 v[0:1], v[0:1], v[26:27]
	v_pk_mul_f32 v[2:3], v[2:3], v[28:29]
	v_cvt_pk_bf16_f32 v128, v0, v1
	v_cvt_pk_bf16_f32 v129, v2, v3
	global_load_dwordx4 v[0:3], v[188:189], off offset:416
	s_nop 0
	global_load_dwordx2 v[20:21], v[68:69], off offset:224
	s_waitcnt vmcnt(2)
	v_lshlrev_b32_e32 v22, 16, v24
	v_and_b32_e32 v23, 0xffff0000, v24
	v_lshlrev_b32_e32 v24, 16, v25
	v_and_b32_e32 v25, 0xffff0000, v25
	v_mul_f32_e32 v11, 0xbfb8aa3b, v22
	v_mul_f32_e32 v26, 0xbfb8aa3b, v23
	v_mul_f32_e32 v27, 0xbfb8aa3b, v24
	v_mul_f32_e32 v28, 0xbfb8aa3b, v25
	v_exp_f32_e32 v11, v11
	v_exp_f32_e32 v26, v26
	v_exp_f32_e32 v27, v27
	v_exp_f32_e32 v28, v28
	v_add_f32_e32 v11, 1.0, v11
	v_add_f32_e32 v29, 1.0, v26
	v_add_f32_e32 v30, 1.0, v27
	v_add_f32_e32 v31, 1.0, v28
	v_rcp_f32_e32 v26, v11
	v_rcp_f32_e32 v27, v29
	v_rcp_f32_e32 v28, v30
	v_rcp_f32_e32 v29, v31
	v_pk_mul_f32 v[18:19], v[18:19], v[10:11] op_sel_hi:[1,0]
	v_pk_mul_f32 v[16:17], v[16:17], v[10:11] op_sel_hi:[1,0]
	v_pk_mul_f32 v[22:23], v[26:27], v[22:23]
	v_pk_mul_f32 v[24:25], v[28:29], v[24:25]
	s_waitcnt vmcnt(1)
	v_pk_mul_f32 v[0:1], v[18:19], v[0:1]
	v_pk_mul_f32 v[2:3], v[16:17], v[2:3]
	v_pk_mul_f32 v[0:1], v[0:1], v[22:23]
	v_pk_mul_f32 v[2:3], v[2:3], v[24:25]
	v_cvt_pk_bf16_f32 v130, v0, v1
	v_cvt_pk_bf16_f32 v131, v2, v3
	s_nop 1
	v_permlane32_swap_b32 v128, v130
	v_permlane32_swap_b32 v129, v131
	global_store_dwordx4 v[132:133], v[128:131], off offset:192
	global_load_dwordx4 v[0:3], v[188:189], off offset:448
	s_nop 0
	global_load_dwordx2 v[16:17], v[68:69], off offset:240
	s_waitcnt vmcnt(3)
	v_lshlrev_b32_e32 v18, 16, v20
	v_and_b32_e32 v19, 0xffff0000, v20
	v_lshlrev_b32_e32 v20, 16, v21
	v_and_b32_e32 v21, 0xffff0000, v21
	v_mul_f32_e32 v11, 0xbfb8aa3b, v18
	v_mul_f32_e32 v22, 0xbfb8aa3b, v19
	v_mul_f32_e32 v23, 0xbfb8aa3b, v20
	v_mul_f32_e32 v24, 0xbfb8aa3b, v21
	v_exp_f32_e32 v11, v11
	v_exp_f32_e32 v22, v22
	v_exp_f32_e32 v23, v23
	v_exp_f32_e32 v24, v24
	v_add_f32_e32 v11, 1.0, v11
	v_add_f32_e32 v25, 1.0, v22
	v_add_f32_e32 v26, 1.0, v23
	v_add_f32_e32 v27, 1.0, v24
	v_rcp_f32_e32 v22, v11
	v_rcp_f32_e32 v23, v25
	v_rcp_f32_e32 v24, v26
	v_rcp_f32_e32 v25, v27
	v_pk_mul_f32 v[6:7], v[6:7], v[10:11] op_sel_hi:[1,0]
	v_pk_mul_f32 v[4:5], v[4:5], v[10:11] op_sel_hi:[1,0]
	v_pk_mul_f32 v[18:19], v[22:23], v[18:19]
	v_pk_mul_f32 v[20:21], v[24:25], v[20:21]
	s_waitcnt vmcnt(1)
	v_pk_mul_f32 v[0:1], v[6:7], v[0:1]
	v_pk_mul_f32 v[2:3], v[4:5], v[2:3]
	v_pk_mul_f32 v[0:1], v[0:1], v[18:19]
	v_pk_mul_f32 v[2:3], v[2:3], v[20:21]
	v_cvt_pk_bf16_f32 v128, v0, v1
	v_cvt_pk_bf16_f32 v129, v2, v3
	global_load_dwordx4 v[0:3], v[188:189], off offset:480
	s_waitcnt vmcnt(1)
	v_lshlrev_b32_e32 v4, 16, v16
	v_and_b32_e32 v5, 0xffff0000, v16
	v_lshlrev_b32_e32 v6, 16, v17
	v_and_b32_e32 v7, 0xffff0000, v17
	v_mul_f32_e32 v11, 0xbfb8aa3b, v4
	v_mul_f32_e32 v16, 0xbfb8aa3b, v5
	v_mul_f32_e32 v17, 0xbfb8aa3b, v6
	v_mul_f32_e32 v18, 0xbfb8aa3b, v7
	v_exp_f32_e32 v11, v11
	v_exp_f32_e32 v16, v16
	v_exp_f32_e32 v17, v17
	v_exp_f32_e32 v18, v18
	v_add_f32_e32 v11, 1.0, v11
	v_add_f32_e32 v19, 1.0, v16
	v_add_f32_e32 v20, 1.0, v17
	v_add_f32_e32 v21, 1.0, v18
	v_rcp_f32_e32 v16, v11
	v_rcp_f32_e32 v17, v19
	v_rcp_f32_e32 v18, v20
	v_rcp_f32_e32 v19, v21
	v_pk_mul_f32 v[12:13], v[12:13], v[10:11] op_sel_hi:[1,0]
	v_pk_mul_f32 v[10:11], v[14:15], v[10:11] op_sel_hi:[1,0]
	v_pk_mul_f32 v[4:5], v[16:17], v[4:5]
	v_pk_mul_f32 v[6:7], v[18:19], v[6:7]
	s_waitcnt vmcnt(0)
	v_pk_mul_f32 v[0:1], v[12:13], v[0:1]
	v_pk_mul_f32 v[2:3], v[10:11], v[2:3]
	v_pk_mul_f32 v[0:1], v[0:1], v[4:5]
	v_pk_mul_f32 v[2:3], v[2:3], v[6:7]
	v_cvt_pk_bf16_f32 v130, v0, v1
	v_cvt_pk_bf16_f32 v131, v2, v3
	s_nop 1
	v_permlane32_swap_b32 v128, v130
	v_permlane32_swap_b32 v129, v131
	global_store_dwordx4 v[132:133], v[128:131], off offset:224
